# P2 work queue: next item index prefetched one item ahead (atomic latency hidden behind the current item)
# baseline (speedup 1.0000x reference)
.LBB0_243:
	s_or_b64 exec, exec, s[0:1]
	s_waitcnt lgkmcnt(0)
	v_mov_b32_e32 v0, v254
	s_barrier
	s_mov_b32 s0, 0x46800000
	v_and_b32_e32 v1, 63, v0
	v_lshlrev_b32_e32 v1, 2, v1
	global_load_dword v2, v1, s[24:25]
	global_load_dword v3, v1, s[26:27]
	global_load_dword v4, v1, s[36:37]
	global_load_dword v5, v1, s[38:39]
	global_load_dword v6, v1, s[20:21]
	global_load_dword v7, v1, s[22:23]
	v_mbcnt_lo_u32_b32 v1, -1, 0
	v_mbcnt_hi_u32_b32 v1, -1, v1
	v_and_b32_e32 v8, 64, v1
	v_xor_b32_e32 v9, 1, v1
	v_add_u32_e32 v8, 64, v8
	v_xor_b32_e32 v10, 2, v1
	v_cmp_lt_i32_e32 vcc, v9, v8
	v_xor_b32_e32 v11, 4, v1
	v_xor_b32_e32 v12, 8, v1
	v_cndmask_b32_e32 v9, v1, v9, vcc
	v_cmp_lt_i32_e32 vcc, v10, v8
	v_xor_b32_e32 v13, 16, v1
	v_xor_b32_e32 v14, 32, v1
	v_cndmask_b32_e32 v10, v1, v10, vcc
	v_cmp_lt_i32_e32 vcc, v11, v8
	s_add_u32 s38, s52, 0x3800000
	s_addc_u32 s44, s53, 0
	v_cndmask_b32_e32 v11, v1, v11, vcc
	v_cmp_lt_i32_e32 vcc, v12, v8
	s_add_u32 s45, s52, 0x4800000
	s_addc_u32 s46, s53, 0
	v_cndmask_b32_e32 v12, v1, v12, vcc
	v_cmp_lt_i32_e32 vcc, v13, v8
	s_add_u32 s47, s52, 0x5800000
	s_addc_u32 s48, s53, 0
	v_cndmask_b32_e32 v13, v1, v13, vcc
	v_cmp_lt_i32_e32 vcc, v14, v8
	v_lshlrev_b32_e32 v8, 2, v9
	v_lshlrev_b32_e32 v9, 2, v10
	v_cndmask_b32_e32 v1, v1, v14, vcc
	v_lshlrev_b32_e32 v10, 2, v11
	v_lshlrev_b32_e32 v11, 2, v12
	v_lshlrev_b32_e32 v193, 2, v13
	v_lshlrev_b32_e32 v194, 2, v1
	s_add_u32 s49, s52, 0x6800000
	s_addc_u32 s50, s53, 0
	s_add_u32 s51, s52, 0x7800000
	s_addc_u32 s56, s53, 0
	s_add_u32 s57, s52, 0x8800000
	s_addc_u32 s58, s53, 0
	s_add_u32 s16, s52, 0xb800000
	s_mov_b32 s21, 0
	s_mov_b32 s39, 0x3fb8aa3b
	s_addc_u32 s17, s53, 0
	v_mov_b32_e32 v131, 0
	s_add_i32 s63, 0, 0x20040
	s_movk_i32 s64, 0x70
	v_mov_b32_e32 v195, 0x358637bd
	s_mov_b32 s65, 0x800000
	s_movk_i32 s66, 0xffef
	s_movk_i32 s67, 0xffe7
	v_mov_b32_e32 v196, 0x3f80
	v_mov_b32_e32 v197, 0x3f803f80
	v_mov_b32_e32 v198, 0x42800000
	v_mov_b32_e32 v199, 0xc6ea6000
	s_waitcnt vmcnt(4)
	v_mul_f32_e32 v1, v2, v3
	ds_bpermute_b32 v1, v8, v1
	s_waitcnt vmcnt(2)
	v_mul_f32_e32 v12, v4, v5
	s_waitcnt vmcnt(1)
	v_and_b32_e32 v13, 0x7fffffff, v6
	s_waitcnt vmcnt(0)
	v_and_b32_e32 v14, 0x7fffffff, v7
	ds_bpermute_b32 v12, v8, v12
	ds_bpermute_b32 v13, v8, v13
	ds_bpermute_b32 v8, v8, v14
	v_max_f32_e64 v6, |v6|, |v6|
	s_waitcnt lgkmcnt(3)
	v_fmac_f32_e32 v1, v2, v3
	s_waitcnt lgkmcnt(2)
	v_fmac_f32_e32 v12, v4, v5
	s_waitcnt lgkmcnt(1)
	v_max_f32_e32 v2, v13, v13
	v_max_f32_e64 v7, |v7|, |v7|
	s_waitcnt lgkmcnt(0)
	v_max_f32_e32 v3, v8, v8
	ds_bpermute_b32 v4, v9, v1
	ds_bpermute_b32 v5, v9, v12
	v_max_f32_e32 v2, v6, v2
	v_max_f32_e32 v3, v7, v3
	ds_bpermute_b32 v6, v9, v2
	ds_bpermute_b32 v7, v9, v3
	s_waitcnt lgkmcnt(3)
	v_add_f32_e32 v1, v1, v4
	s_waitcnt lgkmcnt(2)
	v_add_f32_e32 v4, v12, v5
	ds_bpermute_b32 v5, v10, v1
	ds_bpermute_b32 v8, v10, v4
	s_waitcnt lgkmcnt(3)
	v_max_f32_e32 v6, v6, v6
	s_waitcnt lgkmcnt(2)
	v_max_f32_e32 v7, v7, v7
	v_max_f32_e32 v2, v2, v6
	v_max_f32_e32 v3, v3, v7
	ds_bpermute_b32 v6, v10, v2
	ds_bpermute_b32 v7, v10, v3
	s_waitcnt lgkmcnt(3)
	v_add_f32_e32 v1, v1, v5
	s_waitcnt lgkmcnt(2)
	v_add_f32_e32 v4, v4, v8
	ds_bpermute_b32 v5, v11, v1
	ds_bpermute_b32 v8, v11, v4
	s_waitcnt lgkmcnt(3)
	v_max_f32_e32 v6, v6, v6
	s_waitcnt lgkmcnt(2)
	v_max_f32_e32 v7, v7, v7
	v_max_f32_e32 v2, v2, v6
	v_max_f32_e32 v3, v3, v7
	ds_bpermute_b32 v6, v11, v2
	ds_bpermute_b32 v7, v11, v3
	s_waitcnt lgkmcnt(3)
	v_add_f32_e32 v1, v1, v5
	s_waitcnt lgkmcnt(2)
	v_add_f32_e32 v4, v4, v8
	ds_bpermute_b32 v5, v193, v1
	ds_bpermute_b32 v8, v193, v4
	s_waitcnt lgkmcnt(3)
	v_max_f32_e32 v6, v6, v6
	s_waitcnt lgkmcnt(2)
	v_max_f32_e32 v7, v7, v7
	v_max_f32_e32 v2, v2, v6
	v_max_f32_e32 v3, v3, v7
	ds_bpermute_b32 v6, v193, v2
	ds_bpermute_b32 v7, v193, v3
	s_waitcnt lgkmcnt(3)
	v_add_f32_e32 v1, v1, v5
	s_waitcnt lgkmcnt(2)
	v_add_f32_e32 v4, v4, v8
	ds_bpermute_b32 v5, v194, v1
	ds_bpermute_b32 v8, v194, v4
	s_waitcnt lgkmcnt(3)
	v_max_f32_e32 v6, v6, v6
	s_waitcnt lgkmcnt(2)
	v_max_f32_e32 v7, v7, v7
	v_max_f32_e32 v2, v2, v6
	v_max_f32_e32 v3, v3, v7
	s_waitcnt lgkmcnt(1)
	v_add_f32_e32 v1, v1, v5
	s_waitcnt lgkmcnt(0)
	v_add_f32_e32 v4, v4, v8
	ds_bpermute_b32 v5, v194, v2
	ds_bpermute_b32 v6, v194, v3
	v_mul_f32_e32 v1, 0x3fb8aa3b, v1
	v_mul_f32_e32 v4, 0x3fb8aa3b, v4
	v_exp_f32_e32 v1, v1
	v_exp_f32_e32 v4, v4
	s_waitcnt lgkmcnt(1)
	v_max_f32_e32 v5, v5, v5
	s_waitcnt lgkmcnt(0)
	v_max_f32_e32 v6, v6, v6
	v_max_f32_e32 v2, v2, v5
	v_sub_f32_e32 v1, v1, v4
	v_max_f32_e32 v3, v3, v6
	v_add_f32_e32 v180, 0x3e4ccccd, v1
	v_mul_f32_e32 v1, 0x41000000, v2
	v_mul_f32_e32 v1, v1, v3
	v_mul_f32_e32 v1, 0x3f828f5c, v1
	v_mov_b32_e32 v2, 0x41c80000
	v_fmac_f32_e32 v2, 2.0, v1
	v_mul_f32_e32 v1, 4.0, v2
	v_ceil_f32_e32 v1, v1
	v_mov_b32_e32 v3, 0x46800000
	v_cmp_nle_f32_e32 vcc, s0, v1
	v_mov_b32_e32 v181, v180
	s_nop 0
	v_cndmask_b32_e32 v1, v3, v1, vcc
	s_nop 0
	v_readfirstlane_b32 s59, v1
	v_mul_f32_e32 v1, 0x41800000, v2
	v_ceil_f32_e32 v1, v1
	v_cmp_nle_f32_e32 vcc, s0, v1
	s_nop 1
	v_cndmask_b32_e32 v1, v3, v1, vcc
	s_nop 0
	v_readfirstlane_b32 s60, v1
	v_mul_f32_e32 v1, 0x42800000, v2
	v_ceil_f32_e32 v1, v1
	v_cmp_nle_f32_e32 vcc, s0, v1
	s_nop 1
	v_cndmask_b32_e32 v1, v3, v1, vcc
	s_nop 0
	v_readfirstlane_b32 s61, v1
	v_mul_f32_e32 v1, 0x43800000, v2
	v_ceil_f32_e32 v1, v1
	v_cmp_nle_f32_e32 vcc, s0, v1
	v_cmp_eq_u32_e64 s[0:1], 0, v0
	s_nop 0
	v_cndmask_b32_e32 v1, v3, v1, vcc
	s_nop 0
	v_readfirstlane_b32 s62, v1
	s_and_saveexec_b64 s[4:5], s[0:1]
	v_mov_b32_e32 v243, 1
	global_atomic_add v242, v131, v243, s[52:53] sc0
	s_or_b64 exec, exec, s[4:5]
	s_branch .LBB0_246

.LBB0_246:
	s_and_saveexec_b64 s[4:5], s[0:1]
	s_cbranch_execz .LBB0_250
	s_waitcnt vmcnt(0)
	v_mov_b32_e32 v0, v242
	v_mov_b32_e32 v1, s63
	v_mov_b32_e32 v243, 1
	ds_write_b32 v1, v0
	global_atomic_add v242, v131, v243, s[52:53] sc0
